# attnB unit prologue: V0/K1 DMA issued behind the Q loads, first barrier waits vmcnt(4); compiler vmcnt(0) before first QK MFMA relaxed to vmcnt(8)
# speedup vs baseline: 1.0137x; 1.0024x over previous
; #define DMA_K(t, slot) do { _Pragma("unroll") for (int i_ = 0; i_ < 2; ++i_) __builtin_amdgcn_global_load_lds((const unsigned*)(ksrc[i_] + (size_t)(t) * 64 * DM), (LAS unsigned*)(lds3 + (slot) + (i_ * 8 + wid) * 1024), 16, 0, 0); } while (0)
; #define DMA_V(t, slot) do { _Pragma("unroll") for (int i_ = 0; i_ < 2; ++i_) __builtin_amdgcn_global_load_lds((const unsigned*)(vsrc[i_] + (size_t)(t) * 64 * DM), (LAS unsigned*)(lds3 + RING + (slot) + (i_ * 8 + wid) * 1024), 16, 0, 0); } while (0)
; __device__ __forceinline__ void attnB_unit(const bf16* Q, const bf16* __restrict__ K, const bf16* __restrict__ V, bf16* O, long rowbase, int seq, int h, int q0, float lam, char* lds, LAS unsigned char* lds3) {
;     ...
;     for (int i = 0; i < 2; ++i) { const int q = (i * 8 + wid) * 64 + lane;
;         { const int row = q >> 4, lc = (q & 15) ^ (row & 7); ksrc[i] = K + (size_t)(rowbase + row) * DM + h * 128 + lc * 8; }
;         { const int st = q >> 5, w = q & 31, k = (st >> 2) * 8 + (w >> 2), cc = (st & 3) * 32 + (w & 3) * 8;
;           vsrc[i] = V + (size_t)(rowbase + k) * DM + h * 128 + cc; } }
;     ...
;     DMA_K(0, 0); DMA_V(0, 0); DMA_K(1, SHM_KV);
;     const bf16* Qw = Q + (size_t)(rowbase + q0 + wq * 32 + r32) * DM + h * 128 + c * 64 + hi * 8;
; #pragma unroll
;     for (int d0 = 0; d0 < 4; ++d0) qr[d0] = *reinterpret_cast<const bf16x8*>(Qw + d0 * 16);
.LBB0_270:
	s_lshr_b32 s8, s4, 7
	s_sext_i32_i16 s0, s5
	v_cvt_f32_ubyte0_e32 v2, s8
	v_cvt_f32_i32_e32 v1, s0
	v_rcp_iflag_f32_e32 v3, v2
	s_ashr_i32 s0, s0, 30
	s_or_b32 s9, s0, 1
	v_mov_b32_e32 v38, v200
	v_mul_f32_e32 v3, v1, v3
	v_trunc_f32_e32 v3, v3
	v_fma_f32 v1, -v3, v2, v1
	v_cvt_i32_f32_e32 v3, v3
	v_cmp_ge_f32_e64 s[0:1], |v1|, v2
	s_and_b64 s[0:1], s[0:1], exec
	s_cselect_b32 s0, s9, 0
	v_readfirstlane_b32 s1, v3
	s_add_i32 s0, s1, s0
	s_sext_i32_i16 s1, s0
	s_mul_i32 s0, s0, s8
	s_sub_i32 s0, s5, s0
	s_sext_i32_i16 s0, s0
	s_lshl_b32 s5, s0, 7
	s_lshl_b32 s0, s1, 7
	v_readfirstlane_b32 s28, v38
	s_ashr_i32 s26, s28, 6
	s_ashr_i32 s1, s0, 31
	s_and_b32 s29, s26, 3
	s_and_b32 s27, s28, 0xffffffc0
	s_lshl_b64 s[0:1], s[0:1], 1
	v_lshlrev_b32_e32 v2, 3, v38
	s_add_u32 s8, s20, s0
	v_and_b32_e32 v114, 24, v2
	v_mov_b32_e32 v2, s28
	s_movk_i32 s47, 0xffc0
	s_addc_u32 s9, s21, s1
	v_bfi_b32 v115, s47, v2, v38
	v_and_b32_e32 v1, 15, v38
	s_add_u32 s18, s22, s0
	v_ashrrev_i32_e32 v2, 4, v115
	v_lshrrev_b32_e32 v8, 2, v38
	s_addc_u32 s19, s23, s1
	v_bitop3_b32 v4, v2, v1, 15 bitop3:0x6c
	s_ashr_i32 s47, s28, 4
	v_ashrrev_i32_e32 v3, 31, v2
	v_lshlrev_b32_e32 v52, 4, v4
	v_bfi_b32 v4, -8, s47, v8
	v_lshl_add_u64 v[2:3], s[2:3], 0, v[2:3]
	v_ashrrev_i32_e32 v5, 31, v4
	v_lshlrev_b64 v[50:51], 11, v[2:3]
	v_lshl_add_u64 v[4:5], s[2:3], 0, v[4:5]
	v_and_b32_e32 v188, 63, v38
	v_lshl_add_u64 v[2:3], s[8:9], 0, v[50:51]
	v_mov_b32_e32 v53, v0
	v_and_or_b32 v6, v115, s62, v114
	v_lshlrev_b64 v[54:55], 11, v[4:5]
	s_addk_i32 s27, 0x200
	v_lshl_add_u64 v[2:3], v[2:3], 0, v[52:53]
	v_lshl_add_u64 v[4:5], s[18:19], 0, v[54:55]
	v_lshlrev_b32_e32 v6, 1, v6
	v_mov_b32_e32 v7, v0
	v_or_b32_e32 v53, s27, v188
	v_lshl_add_u64 v[4:5], v[4:5], 0, v[6:7]
	v_ashrrev_i32_e32 v6, 4, v53
	v_ashrrev_i32_e32 v7, 31, v6
	v_bitop3_b32 v1, v6, v1, 15 bitop3:0x6c
	v_lshl_add_u64 v[6:7], s[2:3], 0, v[6:7]
	v_lshlrev_b64 v[56:57], 11, v[6:7]
	v_lshl_add_u64 v[6:7], s[8:9], 0, v[56:57]
	s_ashr_i32 s8, s27, 4
	v_bfi_b32 v8, -8, s8, v8
	s_lshl_b32 s8, s26, 10
	v_ashrrev_i32_e32 v9, 31, v8
	s_add_i32 s49, s8, 0
	v_mov_b32_e32 v18, v0
	v_mov_b32_e32 v19, v0
	v_mov_b32_e32 v20, v0
	v_mov_b32_e32 v21, v0
	v_mov_b32_e32 v22, v0
	v_mov_b32_e32 v23, v0
	v_mov_b32_e32 v24, v0
	v_mov_b32_e32 v25, v0
	v_mov_b32_e32 v26, v0
	v_mov_b32_e32 v27, v0
	v_mov_b32_e32 v28, v0
	v_mov_b32_e32 v29, v0
	v_mov_b32_e32 v30, v0
	v_mov_b32_e32 v31, v0
	v_mov_b32_e32 v32, v0
	v_mov_b32_e32 v33, v0
	v_lshlrev_b32_e32 v58, 4, v1
	v_mov_b32_e32 v59, v0
	v_lshl_add_u64 v[8:9], s[2:3], 0, v[8:9]
	s_mov_b32 m0, s49
	v_lshl_add_u64 v[6:7], v[6:7], 0, v[58:59]
	v_and_or_b32 v1, v53, s62, v114
	v_lshlrev_b64 v[60:61], 11, v[8:9]
	global_load_lds_dwordx4 v[2:3], off
	s_add_i32 m0, s49, 0x2000
	v_lshl_add_u64 v[8:9], s[18:19], 0, v[60:61]
	v_lshlrev_b32_e32 v10, 1, v1
	v_mov_b32_e32 v11, v0
	global_load_lds_dwordx4 v[6:7], off
	v_lshl_add_u64 v[8:9], v[8:9], 0, v[10:11]
	s_ashr_i32 s47, s28, 8
	s_ashr_i32 s8, s5, 31
	s_add_u32 s2, s2, s5
	s_addc_u32 s3, s3, s8
	s_lshl_b32 s5, s29, 5
	s_add_u32 s2, s5, s2
	v_and_b32_e32 v34, 31, v38
	v_mov_b32_e32 v35, v0
	s_addc_u32 s3, 0, s3
	v_lshl_add_u64 v[10:11], s[2:3], 0, v[34:35]
	v_lshlrev_b64 v[10:11], 11, v[10:11]
	v_lshl_add_u64 v[10:11], s[10:11], 0, v[10:11]
	s_lshl_b32 s2, s47, 6
	v_bfe_u32 v17, v38, 5, 1
	v_lshl_add_u64 v[166:167], v[10:11], 0, s[0:1]
	s_ashr_i32 s3, s2, 31
	v_lshl_add_u64 v[10:11], s[2:3], 1, v[166:167]
	v_lshlrev_b32_e32 v36, 4, v17
	v_mov_b32_e32 v37, v0
	v_lshl_add_u64 v[10:11], v[10:11], 0, v[36:37]
	global_load_dwordx4 v[158:161], v[10:11], off
	global_load_dwordx4 v[154:157], v[10:11], off offset:32
	global_load_dwordx4 v[150:153], v[10:11], off offset:64
	global_load_dwordx4 v[146:149], v[10:11], off offset:96
	s_add_i32 m0, s49, 0xc000
	s_nop 0
	global_load_lds_dwordx4 v[4:5], off
	s_add_i32 m0, s49, 0xe000
	s_nop 0
	global_load_lds_dwordx4 v[8:9], off
	v_lshl_add_u64 v[10:11], v[2:3], 0, s[40:41]
	s_add_i32 m0, s49, 0x4000
	s_nop 0
	global_load_lds_dwordx4 v[10:11], off
	v_lshl_add_u64 v[10:11], v[6:7], 0, s[40:41]
	s_add_i32 m0, s49, 0x6000
	s_nop 0
	global_load_lds_dwordx4 v[10:11], off
	s_waitcnt vmcnt(4) lgkmcnt(0)
	s_barrier
; __device__ __forceinline__ int v_rd_base(int lane) { return ((lane & 3) << 3) | (((lane >> 2) & 3) << 6) | (((lane >> 4) & 1) << 5) | (((lane >> 5) & 1) << 8); }
; #define WAIT_BAR(N) asm volatile("s_waitcnt vmcnt(" #N ") lgkmcnt(0)\n\ts_barrier" ::: "memory")
; #define DMA_K(t, slot) do { _Pragma("unroll") for (int i_ = 0; i_ < 2; ++i_) __builtin_amdgcn_global_load_lds((const unsigned*)(ksrc[i_] + (size_t)(t) * 64 * DM), (LAS unsigned*)(lds3 + (slot) + (i_ * 8 + wid) * 1024), 16, 0, 0); } while (0)
; #define DMA_V(t, slot) do { _Pragma("unroll") for (int i_ = 0; i_ < 2; ++i_) __builtin_amdgcn_global_load_lds((const unsigned*)(vsrc[i_] + (size_t)(t) * 64 * DM), (LAS unsigned*)(lds3 + RING + (slot) + (i_ * 8 + wid) * 1024), 16, 0, 0); } while (0)
; #define ROT() do { const int t_ = sl_prev; sl_prev = sl_cur; sl_cur = sl_next; sl_next = t_; } while (0)
; __device__ __forceinline__ void attnB_unit(const bf16* Q, const bf16* __restrict__ K, const bf16* __restrict__ V, bf16* O, long rowbase, int seq, int h, int q0, float lam, char* lds, LAS unsigned char* lds3) {
;     ...
;     const int vb0 = (int)(uintptr_t)V_lds + v_rd_base(lane);
;     ...
;     f32x16 pA0, pA1, pB0, pB1; float alA, alB; bf16x8 pa0, pa1, pa2, pa3; const int NT = seq / 64; const int colb0 = c * 128;
;     int sl_prev = 2 * SHM_KV, sl_cur = 0, sl_next = SHM_KV;
;     ...
;     WAIT_BAR(0);
;     DMA_K(2, sl_prev); DMA_V(1, sl_next);
;     qkt64n<256>(pA0, pA1, K_lds + sl_cur, qr, r32, hi, colb0, negm); partialSM2<true>(pA0, pA1, m_ref, alA, negm);
;     WAIT_BAR(4); ROT();
	s_add_i32 m0, s49, 0x8000
	v_lshl_add_u64 v[2:3], v[2:3], 0, s[86:87]
	s_lshr_b32 s50, s4, 6
	global_load_lds_dwordx4 v[2:3], off
	s_add_i32 m0, s49, 0xa000
	v_lshl_add_u64 v[2:3], v[6:7], 0, s[86:87]
	s_cmp_lg_u32 0, -1
	global_load_lds_dwordx4 v[2:3], off
	s_cselect_b32 s3, 0, 0
	s_add_i32 m0, s49, 0x10000
	v_lshl_add_u64 v[2:3], v[4:5], 0, s[40:41]
	global_load_lds_dwordx4 v[2:3], off
	v_lshl_add_u64 v[2:3], v[8:9], 0, s[40:41]
	s_add_i32 m0, s49, 0x12000
	v_lshlrev_b32_e32 v37, 4, v38
	global_load_lds_dwordx4 v[2:3], off
	v_lshlrev_b32_e32 v35, 3, v188
	v_and_b32_e32 v39, 0xc0, v37
	v_lshlrev_b32_e32 v38, 1, v38
	v_and_or_b32 v39, v35, 24, v39
	v_and_b32_e32 v38, 32, v38
	v_and_b32_e32 v35, 0x100, v35
	v_or3_b32 v35, v39, v38, v35
	s_add_i32 s3, s3, 0xc000
	v_add_u32_e32 v189, s3, v35
	s_lshl_b32 s3, s47, 7
	v_lshlrev_b32_e32 v191, 8, v34
	v_and_b32_e32 v59, 0xf0, v37
	v_add_u32_e32 v194, 0, v191
	v_or_b32_e32 v78, s3, v36
	v_bitop3_b32 v192, s3, v59, v36 bitop3:0x36
	v_add_u32_e32 v34, v194, v192
	v_bitop3_b32 v193, v78, v59, 32 bitop3:0x36
	ds_read_b128 v[62:65], v34
	ds_read_b128 v[66:69], v34 offset:8192
	v_add_u32_e32 v34, v194, v193
	ds_read_b128 v[70:73], v34
	ds_read_b128 v[74:77], v34 offset:8192
	s_waitcnt lgkmcnt(0)
	s_mov_b32 s2, 0
	s_mov_b32 s52, 4
	s_movk_i32 s51, 0x4000
	s_mov_b32 s48, 0x8000
	v_mov_b32_e32 v1, v0
	v_mov_b32_e32 v2, v0
	v_mov_b32_e32 v3, v0
	v_mov_b32_e32 v4, v0
	v_mov_b32_e32 v5, v0
	v_mov_b32_e32 v6, v0
	v_mov_b32_e32 v7, v0
	v_mov_b32_e32 v8, v0
	v_mov_b32_e32 v9, v0
	v_mov_b32_e32 v10, v0
	v_mov_b32_e32 v11, v0
	v_mov_b32_e32 v12, v0
	v_mov_b32_e32 v13, v0
	v_mov_b32_e32 v14, v0
	v_mov_b32_e32 v15, v0
	s_waitcnt vmcnt(8) lgkmcnt(0)
	v_mfma_f32_32x32x16_bf16 v[34:49], v[62:65], v[158:161], v[18:33]
	v_bitop3_b32 v190, v78, v59, 64 bitop3:0x36
	v_bitop3_b32 v195, v78, v59, s62 bitop3:0x36
	v_add_u32_e32 v59, v194, v195
	v_mfma_f32_32x32x16_bf16 v[18:33], v[66:69], v[158:161], v[18:33]
	v_add_u32_e32 v66, v194, v190
	ds_read_b128 v[62:65], v66
	ds_read_b128 v[66:69], v66 offset:8192
	v_mfma_f32_32x32x16_bf16 v[34:49], v[70:73], v[154:157], v[34:49]
	ds_read_b128 v[70:73], v59
	ds_read_b128 v[78:81], v59 offset:8192
	s_waitcnt lgkmcnt(0)
	v_mfma_f32_32x32x16_bf16 v[18:33], v[74:77], v[154:157], v[18:33]
	s_waitcnt lgkmcnt(3)
	v_mfma_f32_32x32x16_bf16 v[34:49], v[62:65], v[150:153], v[34:49]
	v_or_b32_e32 v56, v56, v58
	v_or_b32_e32 v50, v50, v52
	v_lshl_add_u64 v[172:173], s[14:15], 0, v[56:57]
	v_lshl_add_u64 v[174:175], s[14:15], 0, v[50:51]
	v_mov_b32_e32 v196, 0
	s_waitcnt lgkmcnt(1)
	v_mfma_f32_32x32x16_bf16 v[34:49], v[70:73], v[146:149], v[34:49]
	v_mfma_f32_32x32x16_bf16 v[18:33], v[66:69], v[150:153], v[18:33]
	s_nop 10
	v_max_f32_e32 v59, v35, v35
	v_max_f32_e32 v62, v34, v34
	v_max_f32_e32 v59, v62, v59
	v_max3_f32 v59, v59, v36, v37
	v_max3_f32 v59, v59, v38, v39
	v_max3_f32 v59, v59, v40, v41
	v_max3_f32 v59, v59, v42, v43
	s_waitcnt lgkmcnt(0)
	v_mfma_f32_32x32x16_bf16 v[18:33], v[78:81], v[146:149], v[18:33]
	v_max3_f32 v59, v59, v44, v45
	v_max3_f32 v59, v59, v46, v47
	v_max3_f32 v59, v59, v48, v49
	v_mov_b64_e32 v[80:81], v[14:15]
	v_mov_b64_e32 v[78:79], v[12:13]
	v_mov_b64_e32 v[76:77], v[10:11]
	v_mov_b64_e32 v[74:75], v[8:9]
	s_nop 4
	v_max3_f32 v59, v59, v18, v19
	v_max3_f32 v59, v59, v20, v21
	v_max3_f32 v59, v59, v22, v23
	v_max3_f32 v59, v59, v24, v25
	v_max3_f32 v59, v59, v26, v27
	v_max3_f32 v59, v59, v28, v29
	v_max3_f32 v59, v59, v30, v31
	v_max3_f32 v59, v59, v32, v33
	v_mov_b32_e32 v62, v59
	s_nop 1
	v_permlane32_swap_b32_e32 v59, v62
	v_max_f32_e32 v62, v62, v62
	v_max_f32_e32 v59, v59, v59
	v_max_f32_e32 v59, v59, v62
	v_sub_f32_e32 v98, v18, v59
	v_sub_f32_e32 v18, v34, v59
	v_exp_f32_e32 v212, v18
	v_sub_f32_e32 v18, v35, v59
	v_exp_f32_e32 v216, v18
	v_sub_f32_e32 v18, v36, v59
	v_exp_f32_e32 v213, v18
	v_sub_f32_e32 v18, v37, v59
	v_exp_f32_e32 v217, v18
	v_sub_f32_e32 v18, v38, v59
	v_exp_f32_e32 v214, v18
	v_sub_f32_e32 v18, v39, v59
	v_exp_f32_e32 v218, v18
	v_sub_f32_e32 v18, v40, v59
	v_exp_f32_e32 v215, v18
	v_sub_f32_e32 v18, v41, v59
	v_exp_f32_e32 v219, v18
	v_sub_f32_e32 v18, v42, v59
	v_exp_f32_e32 v197, v18
	v_sub_f32_e32 v18, v43, v59
	v_exp_f32_e32 v208, v18
	v_sub_f32_e32 v18, v44, v59
	v_exp_f32_e32 v198, v18
	v_sub_f32_e32 v18, v45, v59
	v_exp_f32_e32 v209, v18
	v_sub_f32_e32 v18, v46, v59
	v_exp_f32_e32 v199, v18
	v_sub_f32_e32 v18, v47, v59
	v_exp_f32_e32 v210, v18
	v_sub_f32_e32 v18, v48, v59
	v_exp_f32_e32 v207, v18
	v_sub_f32_e32 v18, v49, v59
	v_exp_f32_e32 v211, v18
	v_lshlrev_b32_e32 v18, 1, v115
	v_add_f32_e32 v162, 0, v59
	v_sub_f32_e32 v99, v19, v59
	v_and_b32_e32 v18, 0xc0, v18
	v_lshlrev_b32_e32 v19, 1, v114
	v_xor_b32_e32 v82, 0x80000000, v162
	v_or3_b32 v54, v18, v19, v54
	v_lshlrev_b32_e32 v18, 1, v53
	v_mov_b32_e32 v83, v82
	v_mov_b32_e32 v84, v82
	v_mov_b32_e32 v85, v82
	v_mov_b32_e32 v86, v82
	v_mov_b32_e32 v87, v82
	v_mov_b32_e32 v88, v82
	v_mov_b32_e32 v89, v82
	v_mov_b32_e32 v90, v82
	v_mov_b32_e32 v91, v82
	v_mov_b32_e32 v92, v82
	v_mov_b32_e32 v93, v82
	v_mov_b32_e32 v94, v82
	v_mov_b32_e32 v95, v82
	v_mov_b32_e32 v96, v82
	v_mov_b32_e32 v97, v82
	v_and_b32_e32 v18, 0xc0, v18
	s_waitcnt vmcnt(4) lgkmcnt(0)
	s_barrier
	v_or3_b32 v60, v18, v19, v60
	v_sub_f32_e32 v113, v33, v59
	v_sub_f32_e32 v112, v32, v59
	v_sub_f32_e32 v111, v31, v59
	v_sub_f32_e32 v110, v30, v59
	v_sub_f32_e32 v109, v29, v59
	v_sub_f32_e32 v108, v28, v59
	v_sub_f32_e32 v107, v27, v59
	v_sub_f32_e32 v106, v26, v59
	v_sub_f32_e32 v105, v25, v59
	v_sub_f32_e32 v104, v24, v59
	v_sub_f32_e32 v103, v23, v59
	v_sub_f32_e32 v102, v22, v59
	v_sub_f32_e32 v101, v21, v59
	v_sub_f32_e32 v100, v20, v59
	v_lshl_add_u64 v[168:169], s[14:15], 0, v[54:55]
	v_lshl_add_u64 v[170:171], s[14:15], 0, v[60:61]
	v_mov_b64_e32 v[64:65], v[14:15]
	v_mov_b64_e32 v[48:49], v[14:15]
	v_mov_b64_e32 v[32:33], v[14:15]
	v_mov_b64_e32 v[72:73], v[6:7]
	v_mov_b64_e32 v[70:71], v[4:5]
	v_mov_b64_e32 v[68:69], v[2:3]
	v_mov_b64_e32 v[66:67], v[0:1]
	v_mov_b64_e32 v[62:63], v[12:13]
	v_mov_b64_e32 v[60:61], v[10:11]
	v_mov_b64_e32 v[58:59], v[8:9]
	v_mov_b64_e32 v[56:57], v[6:7]
	v_mov_b64_e32 v[54:55], v[4:5]
	v_mov_b64_e32 v[52:53], v[2:3]
	v_mov_b64_e32 v[50:51], v[0:1]
	v_mov_b64_e32 v[46:47], v[12:13]
	v_mov_b64_e32 v[44:45], v[10:11]
	v_mov_b64_e32 v[42:43], v[8:9]
	v_mov_b64_e32 v[40:41], v[6:7]
	v_mov_b64_e32 v[38:39], v[4:5]
	v_mov_b64_e32 v[36:37], v[2:3]
	v_mov_b64_e32 v[34:35], v[0:1]
	v_mov_b64_e32 v[30:31], v[12:13]
	v_mov_b64_e32 v[28:29], v[10:11]
	v_mov_b64_e32 v[26:27], v[8:9]
	v_mov_b64_e32 v[24:25], v[6:7]
	v_mov_b64_e32 v[22:23], v[4:5]
	v_mov_b64_e32 v[20:21], v[2:3]
	v_mov_b64_e32 v[18:19], v[0:1]
